# P2 power-phase interleave: odd workgroups run their NA unit before their diff-attention unit (SGPRs parked in v243/v242 lanes, own guard poll)
# speedup vs baseline: 1.0014x; 1.0010x over previous
; __global__ void __launch_bounds__(NWAVES * 64, 2) mega_fwd(Args args) {
;     ...
;     if (IN(2)) {
;         const float d1 = wave_sum(lq1[lane] * lk1[lane]), d2 = wave_sum(lq2[lane] * lk2[lane]);
;         const float lam = expf(d1) - expf(d2) + 0.2f;
;         const att::SideJob SJ{w_out, w_up, w_dn, g_mlp, WOUT, WUP, WDN, vcu, 256, (G == 256) ? 36 : 0};
;         for (int u = vcu; u < BATCH * NHEAD * 16; u += G) {
;             const int bh = u >> 4, qb = u & 15;
;             datt::diff_unit2<8>(PROJ, KBI, VBI, out, MIX, subg, lam, bh >> 3, bh & 7, qb, (char*)lds + RING_OFF, SJ, (const unsigned*)(ctl + CW_P1D), (G == 256 && N_LAUNCHES != PER_PHASE) ? 256u : 0u);
.LBB0_395:
	v_readlane_b32 s4, v242, 6
	v_readlane_b32 s5, v242, 7
	s_cmp_lt_i32 s4, 3
	s_cselect_b64 s[0:1], -1, 0
	s_cmp_gt_i32 s5, 2
	s_cselect_b64 s[2:3], -1, 0
	s_and_b64 s[0:1], s[0:1], s[2:3]
	s_andn2_b64 vcc, exec, s[0:1]
	s_cbranch_vccnz .LBB0_628
	v_writelane_b32 v242, 0, 62
	s_bitcmp1_b32 s76, 0
	s_cbranch_scc1 .Lp2_nafirst
.Lp2_diff_entry:
	v_lshlrev_b32_e32 v1, 2, v194
	global_load_dword v2, v1, s[14:15]
	global_load_dword v3, v1, s[16:17]
	global_load_dword v4, v1, s[18:19]
	global_load_dword v5, v1, s[20:21]
	v_mbcnt_lo_u32_b32 v1, -1, 0
	v_mbcnt_hi_u32_b32 v6, -1, v1
	v_and_b32_e32 v1, 64, v6
	v_xor_b32_e32 v7, 1, v6
	s_waitcnt vmcnt(0)
	v_add_u32_e32 v13, 64, v1
	v_cmp_lt_i32_e32 vcc, v7, v13
	v_xor_b32_e32 v8, 2, v6
	v_xor_b32_e32 v9, 4, v6
	v_cndmask_b32_e32 v1, v6, v7, vcc
	v_lshlrev_b32_e32 v1, 2, v1
	v_cmp_lt_i32_e32 vcc, v8, v13
	v_xor_b32_e32 v10, 8, v6
	v_xor_b32_e32 v11, 16, v6
	v_cndmask_b32_e32 v8, v6, v8, vcc
	v_lshlrev_b32_e32 v182, 2, v8
	v_cmp_lt_i32_e32 vcc, v9, v13
	v_xor_b32_e32 v12, 32, v6
	s_cmpk_gt_i32 s76, 0xff
	s_mov_b32 s1, 0
	v_mul_f32_e32 v7, v2, v3
	ds_bpermute_b32 v7, v1, v7
	v_mul_f32_e32 v14, v4, v5
	ds_bpermute_b32 v14, v1, v14
	s_waitcnt lgkmcnt(1)
	v_fmac_f32_e32 v7, v2, v3
	ds_bpermute_b32 v2, v182, v7
	s_waitcnt lgkmcnt(1)
	v_fmac_f32_e32 v14, v4, v5
	ds_bpermute_b32 v3, v182, v14
	v_cndmask_b32_e32 v4, v6, v9, vcc
	v_lshlrev_b32_e32 v183, 2, v4
	s_waitcnt lgkmcnt(1)
	v_add_f32_e32 v2, v7, v2
	ds_bpermute_b32 v4, v183, v2
	s_waitcnt lgkmcnt(1)
	v_add_f32_e32 v3, v14, v3
	ds_bpermute_b32 v5, v183, v3
	v_cmp_lt_i32_e32 vcc, v10, v13
	s_waitcnt lgkmcnt(1)
	v_add_f32_e32 v2, v2, v4
	v_cndmask_b32_e32 v7, v6, v10, vcc
	v_lshlrev_b32_e32 v184, 2, v7
	s_waitcnt lgkmcnt(0)
	v_add_f32_e32 v3, v3, v5
	ds_bpermute_b32 v4, v184, v2
	ds_bpermute_b32 v5, v184, v3
	v_cmp_lt_i32_e32 vcc, v11, v13
	s_waitcnt lgkmcnt(1)
	v_add_f32_e32 v2, v2, v4
	v_cndmask_b32_e32 v7, v6, v11, vcc
	v_lshlrev_b32_e32 v185, 2, v7
	s_waitcnt lgkmcnt(0)
	v_add_f32_e32 v3, v3, v5
	ds_bpermute_b32 v4, v185, v2
	ds_bpermute_b32 v5, v185, v3
	v_cmp_lt_i32_e32 vcc, v12, v13
	s_waitcnt lgkmcnt(1)
	v_add_f32_e32 v4, v2, v4
	v_cndmask_b32_e32 v6, v6, v12, vcc
	v_lshlrev_b32_e32 v6, 2, v6
	s_waitcnt lgkmcnt(0)
	v_add_f32_e32 v2, v3, v5
	ds_bpermute_b32 v5, v6, v4
	ds_bpermute_b32 v3, v6, v2
	s_cbranch_scc1 .LBB0_574
	s_waitcnt lgkmcnt(1)
	v_add_f32_e32 v4, v4, v5
	s_mov_b32 s0, 0x3fb8aa3b
	v_mul_f32_e32 v5, 0x3fb8aa3b, v4
	v_fma_f32 v6, v4, s0, -v5
	v_rndne_f32_e32 v7, v5
	v_fmac_f32_e32 v6, 0x32a5705f, v4
	v_sub_f32_e32 v5, v5, v7
	v_add_f32_e32 v5, v5, v6
	v_exp_f32_e32 v5, v5
	v_cvt_i32_f32_e32 v6, v7
	s_waitcnt lgkmcnt(0)
	v_add_f32_e32 v2, v2, v3
	s_mov_b32 s2, 0xc2ce8ed0
	v_cmp_ngt_f32_e32 vcc, s2, v4
	v_ldexp_f32 v3, v5, v6
	v_mul_f32_e32 v5, 0x3fb8aa3b, v2
	v_fma_f32 v6, v2, s0, -v5
	v_rndne_f32_e32 v7, v5
	v_fmac_f32_e32 v6, 0x32a5705f, v2
	v_sub_f32_e32 v5, v5, v7
	v_add_f32_e32 v5, v5, v6
	v_exp_f32_e32 v5, v5
	v_cvt_i32_f32_e32 v6, v7
	s_mov_b32 s3, 0x42b17218
	v_cndmask_b32_e32 v3, 0, v3, vcc
	v_mov_b32_e32 v7, 0x7f800000
	v_cmp_nlt_f32_e32 vcc, s3, v4
	v_readlane_b32 s6, v242, 12
	v_ldexp_f32 v4, v5, v6
	v_cndmask_b32_e32 v3, v7, v3, vcc
	v_cmp_ngt_f32_e32 vcc, s2, v2
	v_readlane_b32 s7, v242, 13
	v_mov_b32_e32 v147, 0
	v_cndmask_b32_e32 v4, 0, v4, vcc
	v_cmp_nlt_f32_e32 vcc, s3, v2
	s_and_b64 s[2:3], s[6:7], exec
	s_cselect_b32 s3, 36, 0
	s_add_u32 s12, s70, 0xe014100
	s_addc_u32 s13, s71, 0
	s_and_b64 s[4:5], s[6:7], exec
	s_cselect_b32 s42, 0x100, 0
	s_lshl_b32 s0, s76, 6
	s_and_b32 s43, s0, 0x7c0
	v_cndmask_b32_e32 v2, v7, v4, vcc
	s_add_u32 s44, s70, 0x4002000
	v_sub_f32_e32 v2, v3, v2
	s_addc_u32 s45, s71, 0
	v_add_f32_e32 v186, 0x3e4ccccd, v2
	s_add_u32 s46, s70, 0x500c000
	v_cndmask_b32_e64 v2, 0, 1, s[6:7]
	s_addc_u32 s47, s71, 0
	v_cmp_ne_u32_e64 s[4:5], 1, v2
	s_mov_b64 s[14:15], 0x400
	s_mov_b64 s[16:17], 0x4000
	s_add_i32 s48, 0, 0x1c800
	s_mov_b64 s[18:19], 0x8000
	s_mov_b32 s49, 0x41000000
	s_movk_i32 s78, 0x1000
	v_mov_b32_e32 v187, 0x3727c5ac
	s_mov_b32 s79, s76
	s_branch .LBB0_399
; __global__ void __launch_bounds__(NWAVES * 64, 2) mega_fwd(Args args) {
;     ...
;         for (int u = vcu; u < BATCH * NHEAD * 16; u += G) {
;             const int bh = u >> 4, qb = u & 15;
;             datt::diff_unit2<8>(PROJ, KBI, VBI, out, MIX, subg, lam, bh >> 3, bh & 7, qb, (char*)lds + RING_OFF, SJ, (const unsigned*)(ctl + CW_P1D), (G == 256 && N_LAUNCHES != PER_PHASE) ? 256u : 0u);
;         }
;         for (int u = vcu; u < BATCH * NHEAD * 16; u += G) {
;             const int bh = u >> 4, rg = u & 15;
;             att::na_unit<0>(PROJ, MIX, relb, bh >> 3, bh & 7, rg, (char*)lds + RING_OFF);
;         }
.Lp2_nafirst:
	v_writelane_b32 v243, s0, 0
	v_writelane_b32 v243, s1, 1
	v_writelane_b32 v243, s2, 2
	v_writelane_b32 v243, s3, 3
	v_writelane_b32 v243, s4, 4
	v_writelane_b32 v243, s5, 5
	v_writelane_b32 v243, s6, 6
	v_writelane_b32 v243, s7, 7
	v_writelane_b32 v243, s8, 8
	v_writelane_b32 v243, s9, 9
	v_writelane_b32 v243, s10, 10
	v_writelane_b32 v243, s11, 11
	v_writelane_b32 v243, s12, 12
	v_writelane_b32 v243, s13, 13
	v_writelane_b32 v243, s14, 14
	v_writelane_b32 v243, s15, 15
	v_writelane_b32 v243, s16, 16
	v_writelane_b32 v243, s17, 17
	v_writelane_b32 v243, s18, 18
	v_writelane_b32 v243, s19, 19
	v_writelane_b32 v243, s20, 20
	v_writelane_b32 v243, s21, 21
	v_writelane_b32 v243, s22, 22
	v_writelane_b32 v243, s23, 23
	v_writelane_b32 v243, s24, 24
	v_writelane_b32 v243, s25, 25
	v_writelane_b32 v243, s26, 26
	v_writelane_b32 v243, s27, 27
	v_writelane_b32 v243, s28, 28
	v_writelane_b32 v243, s29, 29
	v_writelane_b32 v243, s30, 30
	v_writelane_b32 v243, s31, 31
	v_writelane_b32 v243, s32, 32
	v_writelane_b32 v243, s33, 33
	v_writelane_b32 v243, s34, 34
	v_writelane_b32 v243, s35, 35
	v_writelane_b32 v243, s36, 36
	v_writelane_b32 v243, s37, 37
	v_writelane_b32 v243, s38, 38
	v_writelane_b32 v243, s39, 39
	v_writelane_b32 v243, s40, 40
	v_writelane_b32 v243, s41, 41
	v_writelane_b32 v243, s42, 42
	v_writelane_b32 v243, s43, 43
	v_writelane_b32 v243, s44, 44
	v_writelane_b32 v243, s45, 45
	v_writelane_b32 v243, s46, 46
	v_writelane_b32 v243, s47, 47
	v_writelane_b32 v243, s48, 48
	v_writelane_b32 v243, s49, 49
	v_writelane_b32 v243, s50, 50
	v_writelane_b32 v243, s51, 51
	v_writelane_b32 v243, s52, 52
	v_writelane_b32 v243, s53, 53
	v_writelane_b32 v243, s54, 54
	v_writelane_b32 v243, s55, 55
	v_writelane_b32 v243, s56, 56
	v_writelane_b32 v243, s57, 57
	v_writelane_b32 v243, s58, 58
	v_writelane_b32 v243, s59, 59
	v_writelane_b32 v243, s60, 60
	v_writelane_b32 v243, s61, 61
	v_writelane_b32 v243, s62, 62
	v_writelane_b32 v243, s63, 63
	v_writelane_b32 v242, s64, 24
	v_writelane_b32 v242, s65, 25
	v_writelane_b32 v242, s66, 26
	v_writelane_b32 v242, s67, 27
	v_writelane_b32 v242, s68, 28
	v_writelane_b32 v242, s69, 29
	v_writelane_b32 v242, s70, 30
	v_writelane_b32 v242, s71, 31
	v_writelane_b32 v242, s72, 32
	v_writelane_b32 v242, s73, 33
	v_writelane_b32 v242, s74, 34
	v_writelane_b32 v242, s75, 35
	v_writelane_b32 v242, s76, 36
	v_writelane_b32 v242, s77, 37
	v_writelane_b32 v242, s78, 38
	v_writelane_b32 v242, s79, 39
	v_writelane_b32 v242, s80, 40
	v_writelane_b32 v242, s81, 41
	v_writelane_b32 v242, s82, 42
	v_writelane_b32 v242, s83, 43
	v_writelane_b32 v242, s84, 44
	v_writelane_b32 v242, s85, 45
	v_writelane_b32 v242, s86, 46
	v_writelane_b32 v242, s87, 47
	v_writelane_b32 v242, s88, 48
	v_writelane_b32 v242, s89, 49
	v_writelane_b32 v242, s90, 50
	v_writelane_b32 v242, s91, 51
	v_writelane_b32 v242, s92, 52
	v_writelane_b32 v242, s93, 53
	v_writelane_b32 v242, s94, 54
	v_writelane_b32 v242, s95, 55
	v_writelane_b32 v242, s96, 56
	v_writelane_b32 v242, s97, 57
	v_writelane_b32 v242, s98, 58
	v_writelane_b32 v242, s99, 59
	v_writelane_b32 v242, s100, 60
	v_writelane_b32 v242, s101, 61
	v_writelane_b32 v242, 1, 62
	s_branch .Lp2_na_entry
.Lp2_after_na:
	v_readlane_b32 s0, v243, 0
	v_readlane_b32 s1, v243, 1
	v_readlane_b32 s2, v243, 2
	v_readlane_b32 s3, v243, 3
	v_readlane_b32 s4, v243, 4
	v_readlane_b32 s5, v243, 5
	v_readlane_b32 s6, v243, 6
	v_readlane_b32 s7, v243, 7
	v_readlane_b32 s8, v243, 8
	v_readlane_b32 s9, v243, 9
	v_readlane_b32 s10, v243, 10
	v_readlane_b32 s11, v243, 11
	v_readlane_b32 s12, v243, 12
	v_readlane_b32 s13, v243, 13
	v_readlane_b32 s14, v243, 14
	v_readlane_b32 s15, v243, 15
	v_readlane_b32 s16, v243, 16
	v_readlane_b32 s17, v243, 17
	v_readlane_b32 s18, v243, 18
	v_readlane_b32 s19, v243, 19
	v_readlane_b32 s20, v243, 20
	v_readlane_b32 s21, v243, 21
	v_readlane_b32 s22, v243, 22
	v_readlane_b32 s23, v243, 23
	v_readlane_b32 s24, v243, 24
	v_readlane_b32 s25, v243, 25
	v_readlane_b32 s26, v243, 26
	v_readlane_b32 s27, v243, 27
	v_readlane_b32 s28, v243, 28
	v_readlane_b32 s29, v243, 29
	v_readlane_b32 s30, v243, 30
	v_readlane_b32 s31, v243, 31
	v_readlane_b32 s32, v243, 32
	v_readlane_b32 s33, v243, 33
	v_readlane_b32 s34, v243, 34
	v_readlane_b32 s35, v243, 35
	v_readlane_b32 s36, v243, 36
	v_readlane_b32 s37, v243, 37
	v_readlane_b32 s38, v243, 38
	v_readlane_b32 s39, v243, 39
	v_readlane_b32 s40, v243, 40
	v_readlane_b32 s41, v243, 41
	v_readlane_b32 s42, v243, 42
	v_readlane_b32 s43, v243, 43
	v_readlane_b32 s44, v243, 44
	v_readlane_b32 s45, v243, 45
	v_readlane_b32 s46, v243, 46
	v_readlane_b32 s47, v243, 47
	v_readlane_b32 s48, v243, 48
	v_readlane_b32 s49, v243, 49
	v_readlane_b32 s50, v243, 50
	v_readlane_b32 s51, v243, 51
	v_readlane_b32 s52, v243, 52
	v_readlane_b32 s53, v243, 53
	v_readlane_b32 s54, v243, 54
	v_readlane_b32 s55, v243, 55
	v_readlane_b32 s56, v243, 56
	v_readlane_b32 s57, v243, 57
	v_readlane_b32 s58, v243, 58
	v_readlane_b32 s59, v243, 59
	v_readlane_b32 s60, v243, 60
	v_readlane_b32 s61, v243, 61
	v_readlane_b32 s62, v243, 62
	v_readlane_b32 s63, v243, 63
	v_readlane_b32 s64, v242, 24
	v_readlane_b32 s65, v242, 25
	v_readlane_b32 s66, v242, 26
	v_readlane_b32 s67, v242, 27
	v_readlane_b32 s68, v242, 28
	v_readlane_b32 s69, v242, 29
	v_readlane_b32 s70, v242, 30
	v_readlane_b32 s71, v242, 31
	v_readlane_b32 s72, v242, 32
	v_readlane_b32 s73, v242, 33
	v_readlane_b32 s74, v242, 34
	v_readlane_b32 s75, v242, 35
	v_readlane_b32 s76, v242, 36
	v_readlane_b32 s77, v242, 37
	v_readlane_b32 s78, v242, 38
	v_readlane_b32 s79, v242, 39
	v_readlane_b32 s80, v242, 40
	v_readlane_b32 s81, v242, 41
	v_readlane_b32 s82, v242, 42
	v_readlane_b32 s83, v242, 43
	v_readlane_b32 s84, v242, 44
	v_readlane_b32 s85, v242, 45
	v_readlane_b32 s86, v242, 46
	v_readlane_b32 s87, v242, 47
	v_readlane_b32 s88, v242, 48
	v_readlane_b32 s89, v242, 49
	v_readlane_b32 s90, v242, 50
	v_readlane_b32 s91, v242, 51
	v_readlane_b32 s92, v242, 52
	v_readlane_b32 s93, v242, 53
	v_readlane_b32 s94, v242, 54
	v_readlane_b32 s95, v242, 55
	v_readlane_b32 s96, v242, 56
	v_readlane_b32 s97, v242, 57
	v_readlane_b32 s98, v242, 58
	v_readlane_b32 s99, v242, 59
	v_readlane_b32 s100, v242, 60
	v_readlane_b32 s101, v242, 61
	v_writelane_b32 v242, 2, 62
	s_branch .Lp2_diff_entry

; __global__ void __launch_bounds__(NWAVES * 64, 2) mega_fwd(Args args) {
;     ...
;         for (int u = vcu; u < BATCH * NHEAD * 16; u += G) {
;             const int bh = u >> 4, rg = u & 15;
;             att::na_unit<0>(PROJ, MIX, relb, bh >> 3, bh & 7, rg, (char*)lds + RING_OFF);
;         }
.LBB0_506:
	v_readlane_b32 s3, v242, 62
	s_cmp_eq_u32 s3, 2
	s_cbranch_scc1 .LBB0_574

; __device__ __forceinline__ int crow(int r, int hi) { return (r & 3) + 8 * (r >> 2) + 4 * hi; }
; __device__ __forceinline__ unsigned cvtpk(float lo, float hi) { unsigned r; asm volatile("v_cvt_pk_bf16_f32 %0, %1, %2" : "=v"(r) : "v"(lo), "v"(hi)); return r; }
; template <int VAR> __device__ __forceinline__ void na_unit(const bf16* __restrict__ proj, bf16* mix, const float* __restrict__ relb, int b, int h, int rg, char* lds) {
;     ...
;   if (hi == 0) li_l[r32] = l_reg; asm volatile("s_waitcnt lgkmcnt(0)" ::: "memory");
;   float rli[16];
; #pragma unroll
;   for (int r = 0; r < 16; ++r) rli[r] = __builtin_amdgcn_rcpf(li_l[crow(r, hi)]);
;   bf16* stg = (bf16*)(lds + wid * 8192);
; #pragma unroll
;   for (int r = 0; r < 16; ++r) { const int orow = crow(r, hi);
; #pragma unroll
;     for (int d0 = 0; d0 < 4; ++d0) stg[orow * 128 + d0 * 32 + r32] = (bf16)(cvtpk(o[d0][r] * rli[r], 0.f) & 0xffffu); }
; template <int THRL> ...
;     ...
;       if (gd_ < need) { unsigned sp_ = 0u; while (__hip_atomic_load(guard, __ATOMIC_RELAXED, __HIP_MEMORY_SCOPE_AGENT) < need && ++sp_ < (1u << 22)) __builtin_amdgcn_s_sleep(2); }
.LBB0_507:
	s_or_b64 exec, exec, s[4:5]
	v_readlane_b32 s98, v242, 62
	s_cmp_eq_u32 s98, 1
	s_cbranch_scc0 .Lna_gd_done
	s_add_u32 s98, s70, 0xe014100
	s_addc_u32 s99, s71, 0
	v_mov_b32_e32 v245, 0
	s_mov_b32 s100, 0
.Lna_gd_spin:
	global_load_dword v244, v245, s[98:99] sc1
	s_add_i32 s100, s100, 1
	s_waitcnt vmcnt(0)
	v_readfirstlane_b32 s101, v244
	s_cmp_ge_u32 s101, 0x100
	s_cbranch_scc1 .Lna_gd_done
	s_cmp_lt_u32 s100, 0x100000
	s_cbranch_scc1 .Lna_gd_spin
.Lna_gd_done:
	s_waitcnt lgkmcnt(0)
	v_lshl_add_u32 v10, v167, 2, s82
	ds_read_b128 v[2:5], v10
	ds_read_b128 v[6:9], v10 offset:32
	v_lshlrev_b32_e32 v83, 10, v161
	s_or_b32 s0, s96, s0
	s_lshl_b32 s2, s97, 7
	s_waitcnt lgkmcnt(1)
	v_rcp_f32_e32 v11, v2
	v_rcp_f32_e32 v12, v3
	v_rcp_f32_e32 v13, v4
	v_rcp_f32_e32 v14, v5
	s_waitcnt lgkmcnt(0)
	v_rcp_f32_e32 v15, v6
	ds_read_b128 v[2:5], v10 offset:64
	v_rcp_f32_e32 v16, v7
	v_rcp_f32_e32 v17, v8
	v_rcp_f32_e32 v82, v9
	ds_read_b128 v[6:9], v10 offset:96
	v_lshlrev_b32_e32 v10, 1, v160
	v_add3_u32 v10, s58, v10, v83
	v_mul_f32_e32 v66, v66, v11
	v_mul_f32_e32 v50, v50, v11
	v_mul_f32_e32 v34, v34, v11
	v_mul_f32_e32 v11, v18, v11
	v_cvt_pk_bf16_f32 v66, v66, v147
	ds_write_b16 v10, v66
	v_cvt_pk_bf16_f32 v50, v50, v147
	ds_write_b16 v10, v50 offset:64
	v_cvt_pk_bf16_f32 v34, v34, v147
	ds_write_b16 v10, v34 offset:128
	v_cvt_pk_bf16_f32 v11, v11, v147
	ds_write_b16 v10, v11 offset:192
	v_mul_f32_e32 v11, v67, v12
	v_cvt_pk_bf16_f32 v11, v11, v147
	ds_write_b16 v10, v11 offset:256
	v_mul_f32_e32 v11, v51, v12
	v_cvt_pk_bf16_f32 v11, v11, v147
	ds_write_b16 v10, v11 offset:320
	v_mul_f32_e32 v11, v35, v12
	v_cvt_pk_bf16_f32 v11, v11, v147
	ds_write_b16 v10, v11 offset:384
	v_mul_f32_e32 v11, v19, v12
	v_cvt_pk_bf16_f32 v11, v11, v147
	ds_write_b16 v10, v11 offset:448
	v_mul_f32_e32 v11, v68, v13
	v_cvt_pk_bf16_f32 v11, v11, v147
	ds_write_b16 v10, v11 offset:512
	v_mul_f32_e32 v11, v52, v13
	v_cvt_pk_bf16_f32 v11, v11, v147
	ds_write_b16 v10, v11 offset:576
	v_mul_f32_e32 v11, v36, v13
	v_cvt_pk_bf16_f32 v11, v11, v147
	ds_write_b16 v10, v11 offset:640
	v_mul_f32_e32 v11, v20, v13
	v_cvt_pk_bf16_f32 v11, v11, v147
	ds_write_b16 v10, v11 offset:704
	v_mul_f32_e32 v11, v69, v14
	v_cvt_pk_bf16_f32 v11, v11, v147
	ds_write_b16 v10, v11 offset:768
	v_mul_f32_e32 v11, v53, v14
	v_cvt_pk_bf16_f32 v11, v11, v147
	ds_write_b16 v10, v11 offset:832
	v_mul_f32_e32 v11, v37, v14
	v_cvt_pk_bf16_f32 v11, v11, v147
	ds_write_b16 v10, v11 offset:896
	v_mul_f32_e32 v11, v21, v14
	v_cvt_pk_bf16_f32 v11, v11, v147
	ds_write_b16 v10, v11 offset:960
	v_mul_f32_e32 v11, v70, v15
	v_cvt_pk_bf16_f32 v11, v11, v147
	ds_write_b16 v10, v11 offset:2048
	v_mul_f32_e32 v11, v54, v15
	v_cvt_pk_bf16_f32 v11, v11, v147
	ds_write_b16 v10, v11 offset:2112
	v_mul_f32_e32 v11, v38, v15
	v_cvt_pk_bf16_f32 v11, v11, v147
	ds_write_b16 v10, v11 offset:2176
	v_mul_f32_e32 v11, v22, v15
	v_cvt_pk_bf16_f32 v11, v11, v147
	ds_write_b16 v10, v11 offset:2240
	v_mul_f32_e32 v11, v71, v16
	v_cvt_pk_bf16_f32 v11, v11, v147
	ds_write_b16 v10, v11 offset:2304
	v_mul_f32_e32 v11, v55, v16
	v_cvt_pk_bf16_f32 v11, v11, v147
	ds_write_b16 v10, v11 offset:2368
	v_mul_f32_e32 v11, v39, v16
	v_cvt_pk_bf16_f32 v11, v11, v147
	ds_write_b16 v10, v11 offset:2432
	v_mul_f32_e32 v11, v23, v16
	v_cvt_pk_bf16_f32 v11, v11, v147
	ds_write_b16 v10, v11 offset:2496
	v_mul_f32_e32 v11, v72, v17
	v_cvt_pk_bf16_f32 v11, v11, v147
	ds_write_b16 v10, v11 offset:2560
	v_mul_f32_e32 v11, v56, v17
	v_cvt_pk_bf16_f32 v11, v11, v147
	ds_write_b16 v10, v11 offset:2624
	v_mul_f32_e32 v11, v40, v17
	v_cvt_pk_bf16_f32 v11, v11, v147
	ds_write_b16 v10, v11 offset:2688
	v_mul_f32_e32 v11, v24, v17
	v_cvt_pk_bf16_f32 v11, v11, v147
	ds_write_b16 v10, v11 offset:2752
	v_mul_f32_e32 v11, v73, v82
	v_cvt_pk_bf16_f32 v11, v11, v147
	ds_write_b16 v10, v11 offset:2816
	v_mul_f32_e32 v11, v57, v82
	v_cvt_pk_bf16_f32 v11, v11, v147
	s_waitcnt lgkmcnt(14)
; __device__ __forceinline__ int crow(int r, int hi) { return (r & 3) + 8 * (r >> 2) + 4 * hi; }
; __device__ __forceinline__ unsigned cvtpk(float lo, float hi) { unsigned r; asm volatile("v_cvt_pk_bf16_f32 %0, %1, %2" : "=v"(r) : "v"(lo), "v"(hi)); return r; }
; __device__ __forceinline__ void st16_wt(void* p, u32x4 v) { asm volatile("global_store_dwordx4 %0, %1, off sc1\n\ts_nop 1" :: "v"(p), "v"(v) : "memory"); }
; template <int VAR> __device__ __forceinline__ void na_unit(const bf16* __restrict__ proj, bf16* mix, const float* __restrict__ relb, int b, int h, int rg, char* lds) {
;     ...
;   for (int r = 0; r < 16; ++r) rli[r] = __builtin_amdgcn_rcpf(li_l[crow(r, hi)]);
;   bf16* stg = (bf16*)(lds + wid * 8192);
; #pragma unroll
;   for (int r = 0; r < 16; ++r) { const int orow = crow(r, hi);
; #pragma unroll
;     for (int d0 = 0; d0 < 4; ++d0) stg[orow * 128 + d0 * 32 + r32] = (bf16)(cvtpk(o[d0][r] * rli[r], 0.f) & 0xffffu); }
;   asm volatile("s_waitcnt lgkmcnt(0)" ::: "memory");
;   bf16* Mw = mix + (tok0 + gr * 64 + 32 * (wid & 1)) * 2048 + 1024 + h * 128;
; #pragma unroll
;   for (int i = 0; i < 8; ++i) { const int row = i * 4 + (lane >> 4), ch = lane & 15;
;     const u32x4 v = *(const u32x4*)(stg + row * 128 + ch * 8); st16_wt(Mw + (long)row * 2048 + ch * 8, v); }
; __global__ void __launch_bounds__(NWAVES * 64, 2) mega_fwd(Args args) {
;     ...
;         for (int u = vcu; u < BATCH * NHEAD * 16; u += G) {
	v_rcp_f32_e32 v2, v2
	ds_write_b16 v10, v11 offset:2880
	v_mul_f32_e32 v11, v41, v82
	v_cvt_pk_bf16_f32 v11, v11, v147
	ds_write_b16 v10, v11 offset:2944
	v_mul_f32_e32 v11, v25, v82
	v_cvt_pk_bf16_f32 v11, v11, v147
	ds_write_b16 v10, v11 offset:3008
	v_mul_f32_e32 v11, v74, v2
	v_cvt_pk_bf16_f32 v11, v11, v147
	v_rcp_f32_e32 v3, v3
	ds_write_b16 v10, v11 offset:4096
	v_mul_f32_e32 v11, v58, v2
	v_cvt_pk_bf16_f32 v11, v11, v147
	ds_write_b16 v10, v11 offset:4160
	v_mul_f32_e32 v11, v42, v2
	v_mul_f32_e32 v2, v26, v2
	v_cvt_pk_bf16_f32 v11, v11, v147
	ds_write_b16 v10, v11 offset:4224
	v_cvt_pk_bf16_f32 v2, v2, v147
	ds_write_b16 v10, v2 offset:4288
	v_mul_f32_e32 v2, v75, v3
	v_cvt_pk_bf16_f32 v2, v2, v147
	ds_write_b16 v10, v2 offset:4352
	v_mul_f32_e32 v2, v59, v3
	v_cvt_pk_bf16_f32 v2, v2, v147
	v_rcp_f32_e32 v4, v4
	ds_write_b16 v10, v2 offset:4416
	v_mul_f32_e32 v2, v43, v3
	v_cvt_pk_bf16_f32 v2, v2, v147
	ds_write_b16 v10, v2 offset:4480
	v_mul_f32_e32 v2, v27, v3
	v_cvt_pk_bf16_f32 v2, v2, v147
	ds_write_b16 v10, v2 offset:4544
	v_mul_f32_e32 v2, v76, v4
	v_cvt_pk_bf16_f32 v2, v2, v147
	ds_write_b16 v10, v2 offset:4608
	v_mul_f32_e32 v2, v60, v4
	v_cvt_pk_bf16_f32 v2, v2, v147
	v_rcp_f32_e32 v5, v5
	ds_write_b16 v10, v2 offset:4672
	v_mul_f32_e32 v2, v44, v4
	v_cvt_pk_bf16_f32 v2, v2, v147
	ds_write_b16 v10, v2 offset:4736
	v_mul_f32_e32 v2, v28, v4
	v_cvt_pk_bf16_f32 v2, v2, v147
	ds_write_b16 v10, v2 offset:4800
	v_mul_f32_e32 v2, v77, v5
	v_cvt_pk_bf16_f32 v2, v2, v147
	ds_write_b16 v10, v2 offset:4864
	v_mul_f32_e32 v2, v61, v5
	v_cvt_pk_bf16_f32 v2, v2, v147
	v_rcp_f32_e32 v6, v6
	ds_write_b16 v10, v2 offset:4928
	v_mul_f32_e32 v2, v45, v5
	v_cvt_pk_bf16_f32 v2, v2, v147
	ds_write_b16 v10, v2 offset:4992
	v_mul_f32_e32 v2, v29, v5
	v_cvt_pk_bf16_f32 v2, v2, v147
	ds_write_b16 v10, v2 offset:5056
	v_mul_f32_e32 v2, v78, v6
	v_cvt_pk_bf16_f32 v2, v2, v147
	ds_write_b16 v10, v2 offset:6144
	v_mul_f32_e32 v2, v62, v6
	v_cvt_pk_bf16_f32 v2, v2, v147
	v_rcp_f32_e32 v7, v7
	ds_write_b16 v10, v2 offset:6208
	v_mul_f32_e32 v2, v46, v6
	v_cvt_pk_bf16_f32 v2, v2, v147
	ds_write_b16 v10, v2 offset:6272
	v_mul_f32_e32 v2, v30, v6
	v_cvt_pk_bf16_f32 v2, v2, v147
	ds_write_b16 v10, v2 offset:6336
	v_mul_f32_e32 v2, v79, v7
	v_cvt_pk_bf16_f32 v2, v2, v147
	ds_write_b16 v10, v2 offset:6400
	v_mul_f32_e32 v2, v63, v7
	v_cvt_pk_bf16_f32 v2, v2, v147
	v_rcp_f32_e32 v8, v8
	ds_write_b16 v10, v2 offset:6464
	v_mul_f32_e32 v2, v47, v7
	v_cvt_pk_bf16_f32 v2, v2, v147
	ds_write_b16 v10, v2 offset:6528
	v_mul_f32_e32 v2, v31, v7
	v_cvt_pk_bf16_f32 v2, v2, v147
	ds_write_b16 v10, v2 offset:6592
	v_mul_f32_e32 v2, v80, v8
	v_cvt_pk_bf16_f32 v2, v2, v147
	ds_write_b16 v10, v2 offset:6656
	v_mul_f32_e32 v2, v64, v8
	v_cvt_pk_bf16_f32 v2, v2, v147
	v_rcp_f32_e32 v9, v9
	ds_write_b16 v10, v2 offset:6720
	v_mul_f32_e32 v2, v48, v8
	v_cvt_pk_bf16_f32 v2, v2, v147
	ds_write_b16 v10, v2 offset:6784
	v_mul_f32_e32 v2, v32, v8
	v_cvt_pk_bf16_f32 v2, v2, v147
	ds_write_b16 v10, v2 offset:6848
	v_mul_f32_e32 v2, v81, v9
	v_cvt_pk_bf16_f32 v2, v2, v147
	ds_write_b16 v10, v2 offset:6912
	v_mul_f32_e32 v2, v65, v9
	v_cvt_pk_bf16_f32 v2, v2, v147
	s_lshl_b64 s[0:1], s[0:1], 12
	ds_write_b16 v10, v2 offset:6976
	v_mul_f32_e32 v2, v49, v9
	s_add_u32 s0, s92, s0
	v_cvt_pk_bf16_f32 v2, v2, v147
	s_addc_u32 s1, s93, s1
	s_lshl_b32 s2, s2, 1
	ds_write_b16 v10, v2 offset:7040
	v_mul_f32_e32 v2, v33, v9
	s_add_u32 s0, s0, s2
	v_cvt_pk_bf16_f32 v2, v2, v147
	ds_write_b16 v10, v2 offset:7104
	s_addc_u32 s1, s1, 0
	v_lshrrev_b32_e32 v10, 4, v149
	v_mov_b32_e32 v149, v147
	v_lshl_add_u64 v[6:7], s[0:1], 0, v[148:149]
	s_mov_b64 s[0:1], 0x800
	v_lshl_add_u32 v11, v151, 1, s58
	v_lshl_add_u64 v[6:7], v[6:7], 0, s[0:1]
	v_lshlrev_b32_e32 v146, 12, v10
	s_waitcnt lgkmcnt(0)
	v_lshl_add_u32 v2, v10, 8, v11
	v_lshl_add_u64 v[8:9], v[6:7], 0, v[146:147]
	ds_read_b128 v[2:5], v2
	s_waitcnt lgkmcnt(0)
	global_store_dwordx4 v[8:9], v[2:5], off sc1
	s_nop 1
	v_or_b32_e32 v8, 4, v10
	v_lshlrev_b32_e32 v146, 12, v8
	v_lshl_add_u32 v2, v8, 8, v11
	v_lshl_add_u64 v[8:9], v[6:7], 0, v[146:147]
	ds_read_b128 v[2:5], v2
	s_waitcnt lgkmcnt(0)
	global_store_dwordx4 v[8:9], v[2:5], off sc1
	s_nop 1
	v_or_b32_e32 v8, 8, v10
	v_lshlrev_b32_e32 v146, 12, v8
	v_lshl_add_u32 v2, v8, 8, v11
	v_lshl_add_u64 v[8:9], v[6:7], 0, v[146:147]
	ds_read_b128 v[2:5], v2
	s_waitcnt lgkmcnt(0)
	global_store_dwordx4 v[8:9], v[2:5], off sc1
	s_nop 1
	v_or_b32_e32 v8, 12, v10
	v_lshlrev_b32_e32 v146, 12, v8
	v_lshl_add_u32 v2, v8, 8, v11
	v_lshl_add_u64 v[8:9], v[6:7], 0, v[146:147]
	ds_read_b128 v[2:5], v2
	s_waitcnt lgkmcnt(0)
	global_store_dwordx4 v[8:9], v[2:5], off sc1
	s_nop 1
	v_or_b32_e32 v8, 16, v10
	v_lshlrev_b32_e32 v146, 12, v8
	v_lshl_add_u32 v2, v8, 8, v11
	v_lshl_add_u64 v[8:9], v[6:7], 0, v[146:147]
	ds_read_b128 v[2:5], v2
	s_waitcnt lgkmcnt(0)
	global_store_dwordx4 v[8:9], v[2:5], off sc1
	s_nop 1
	v_or_b32_e32 v8, 20, v10
	v_lshlrev_b32_e32 v146, 12, v8
	v_lshl_add_u32 v2, v8, 8, v11
	v_lshl_add_u64 v[8:9], v[6:7], 0, v[146:147]
	ds_read_b128 v[2:5], v2
	s_waitcnt lgkmcnt(0)
	global_store_dwordx4 v[8:9], v[2:5], off sc1
	s_nop 1
	v_or_b32_e32 v8, 24, v10
	v_lshlrev_b32_e32 v146, 12, v8
	v_lshl_add_u32 v2, v8, 8, v11
	v_lshl_add_u64 v[8:9], v[6:7], 0, v[146:147]
	ds_read_b128 v[2:5], v2
	s_waitcnt lgkmcnt(0)
	global_store_dwordx4 v[8:9], v[2:5], off sc1
	s_nop 1
	v_or_b32_e32 v8, 28, v10
	v_lshl_add_u32 v2, v8, 8, v11
	v_lshlrev_b32_e32 v146, 12, v8
	ds_read_b128 v[2:5], v2
	v_lshl_add_u64 v[6:7], v[6:7], 0, v[146:147]
	s_waitcnt lgkmcnt(0)
	global_store_dwordx4 v[6:7], v[2:5], off sc1
	s_nop 1
	s_add_i32 s89, s89, s33
	s_add_i32 s3, s3, s50
	s_cmpk_gt_i32 s89, 0xff
	s_cbranch_scc1 .LBB0_574

; __device__ __forceinline__ unsigned xb_ld(unsigned* p)              { return __hip_atomic_load(p, __ATOMIC_RELAXED, __HIP_MEMORY_SCOPE_AGENT); }
; __device__ __forceinline__ void xcd_barrier_complete(unsigned* bar, unsigned x, unsigned& nloc, unsigned& nx) {
;     const unsigned G = gridDim.x * gridDim.y * gridDim.z;
;     unsigned sum, cnt, mine, sp = 0u;
;     for (;;) {
;         sum = 0u; cnt = 0u; mine = 0u;
; #pragma unroll
;         for (unsigned j = 0; j < 16; ++j) { const unsigned c = xb_ld(&bar[XB_XCNT(j)]); sum += c; cnt += (c > 0u) ? 1u : 0u; mine = (j == x) ? c : mine; }
; __device__ __forceinline__ void xcd_barrier(const XcdBarrier& b) {
;     asm volatile("s_waitcnt vmcnt(0)" ::: "memory");
;     __syncthreads();
;     if (threadIdx.x == 0) {
;         unsigned* bar = b.bar;
;         __builtin_amdgcn_s_waitcnt(0);
;         unsigned nloc = b.st[0], nx = b.st[1];
;         if (nloc == 0u) { xcd_barrier_complete(bar, b.x, nloc, nx); b.st[0] = nloc; b.st[1] = nx; }
.LBB0_574:
	v_readlane_b32 s4, v242, 62
	s_cmp_eq_u32 s4, 1
	s_cbranch_scc1 .Lp2_after_na
	v_readlane_b32 s4, v242, 6
	v_readlane_b32 s5, v242, 7
	s_cmp_gt_i32 s5, 3
	s_cbranch_scc0 .LBB0_628
	s_waitcnt vmcnt(0)
	s_waitcnt lgkmcnt(0)
	s_barrier
	s_mov_b64 s[0:1], exec
	v_readlane_b32 s2, v242, 4
	v_readlane_b32 s3, v242, 5
	s_and_b64 s[2:3], s[0:1], s[2:3]
	s_mov_b64 exec, s[2:3]
	s_cbranch_execz .LBB0_627
	s_add_i32 s2, 0, 0x26960
	v_mov_b32_e32 v1, s2
	s_waitcnt vmcnt(0) expcnt(0) lgkmcnt(0)
	ds_read_b32 v3, v1
	s_add_i32 s2, 0, 0x26964
	v_mov_b32_e32 v1, s2
	ds_read_b32 v1, v1
	s_waitcnt lgkmcnt(1)
	v_cmp_ne_u32_e32 vcc, 0, v3
	s_cbranch_vccnz .LBB0_591
	v_readlane_b32 s4, v242, 0
	v_readlane_b32 s5, v242, 1
	s_load_dwordx2 s[2:3], s[4:5], 0x4
	s_add_u32 s4, s70, 0xe004200
	s_addc_u32 s5, s71, 0
	s_add_u32 s6, s70, 0xe004400
	s_addc_u32 s7, s71, 0
	s_add_u32 s8, s70, 0xe004500
	s_addc_u32 s9, s71, 0
	s_add_u32 s10, s70, 0xe004600
	s_addc_u32 s11, s71, 0
	s_add_u32 s12, s70, 0xe004700
	s_addc_u32 s13, s71, 0
	s_add_u32 s14, s70, 0xe004800
	s_addc_u32 s15, s71, 0
	s_add_u32 s16, s70, 0xe004900
	s_addc_u32 s17, s71, 0
	s_add_u32 s18, s70, 0xe004a00
	s_addc_u32 s19, s71, 0
	s_add_u32 s20, s70, 0xe004b00
	s_addc_u32 s21, s71, 0
	s_add_u32 s22, s70, 0xe004c00
	s_addc_u32 s23, s71, 0
	s_add_u32 s24, s70, 0xe004d00
	s_addc_u32 s25, s71, 0
	s_add_u32 s26, s70, 0xe004e00
	s_addc_u32 s27, s71, 0
	s_add_u32 s28, s70, 0xe004f00
	s_addc_u32 s29, s71, 0
	s_add_u32 s30, s70, 0xe005000
	s_addc_u32 s31, s71, 0
	s_add_u32 s34, s70, 0xe005100
	s_addc_u32 s35, s71, 0
	s_add_u32 s36, s70, 0xe005200
	s_addc_u32 s37, s71, 0
	s_waitcnt lgkmcnt(0)
	s_mul_i32 s2, s2, s33
	s_add_u32 s38, s70, 0xe005300
	s_mul_i32 s2, s2, s3
	s_addc_u32 s39, s71, 0
	s_mov_b32 s3, 1
	v_mov_b32_e32 v17, 0
	s_branch .LBB0_579
